# v23 + P1 projection epilogue stores write-through (sc1): outputs do not stay in L2, smaller release-fence writeback
# speedup vs baseline: 1.0024x; 1.0004x over previous
; __device__ __forceinline__ unsigned cvt_pk_bf16(float lo, float hi) { unsigned r; asm volatile("v_cvt_pk_bf16_f32 %0, %1, %2" : "=v"(r) : "v"(lo), "v"(hi)); return r; }
;     __device__ __forceinline__ void operator()(const f32x4 (&acc)[2][2][4][2], const Unit& u, int wr, int wc, int fr, int fq) const {
;         const int pn = u.pn; bf16_t* base; int ldc, colt;
;         if (pn < 20) { base = big + (size_t)(pn >> 2) * BUFE; ldc = 1024; colt = (pn & 3) * 256; }
;         else if (pn == 20) { base = kb; ldc = 256; colt = 0; }
;         else if (pn == 21) { base = vb; ldc = 256; colt = 0; }
;         else { const int q = pn - 22; base = big + (size_t)(5 + (q >> 2)) * BUFE; ldc = 1024; colt = (q & 3) * 256; }
;         const int row0 = u.pm * BM + wr * 64 + fr, col0 = colt + wc * 32 + 8 * fq;
;         const float sc = pn < 4 ? 0.125f * 1.4426950408889634f : 1.0f;
; #pragma unroll
;         for (int ai = 0; ai < 2; ++ai)
; #pragma unroll
;             for (int m = 0; m < 4; ++m) { bf16_t* rowp = base + (size_t)(row0 + ai * HALF + m * 16) * ldc + col0;
; #pragma unroll
;                 for (int bj = 0; bj < 2; ++bj) { const f32x4 v0 = acc[ai][bj][m][0] * sc, v1 = acc[ai][bj][m][1] * sc;
;                     u32x4 w; w.x = cvt_pk_bf16(v0[0], v0[1]); w.y = cvt_pk_bf16(v0[2], v0[3]); w.z = cvt_pk_bf16(v1[0], v1[1]); w.w = cvt_pk_bf16(v1[2], v1[3]);
;                     *(u32x4*)(rowp + bj * HALF) = w; } }
.LBB0_91:
	v_lshl_add_u32 v151, s16, 8, v145
	v_or_b32_e32 v0, s9, v149
	s_cmp_lt_i32 s17, 4
	v_lshl_add_u64 v[146:147], v[0:1], 1, s[40:41]
	v_ashrrev_i32_e32 v0, 31, v151
	s_cselect_b64 vcc, -1, 0
	v_mul_lo_u32 v0, s18, v0
	v_mul_lo_u32 v154, s19, v151
	v_mad_u64_u32 v[152:153], s[16:17], s18, v151, 0
	v_cndmask_b32_e32 v144, 1.0, v194, vcc
	v_add3_u32 v153, v153, v0, v154
	v_lshl_add_u64 v[152:153], v[152:153], 1, v[146:147]
	v_pk_mul_f32 v[128:129], v[144:145], v[128:129] op_sel_hi:[0,1]
	v_pk_mul_f32 v[126:127], v[144:145], v[126:127] op_sel_hi:[0,1]
	v_pk_mul_f32 v[154:155], v[144:145], v[124:125] op_sel_hi:[0,1]
	v_pk_mul_f32 v[124:125], v[144:145], v[122:123] op_sel_hi:[0,1]
	v_cvt_pk_bf16_f32 v122, v126, v127
	v_cvt_pk_bf16_f32 v123, v128, v129
	v_cvt_pk_bf16_f32 v124, v124, v125
	v_cvt_pk_bf16_f32 v125, v154, v155
	global_store_dwordx4 v[152:153], v[122:125], off sc1
	v_pk_mul_f32 v[118:119], v[144:145], v[118:119] op_sel_hi:[0,1]
	v_pk_mul_f32 v[120:121], v[144:145], v[120:121] op_sel_hi:[0,1]
	v_pk_mul_f32 v[122:123], v[144:145], v[112:113] op_sel_hi:[0,1]
	v_pk_mul_f32 v[112:113], v[144:145], v[110:111] op_sel_hi:[0,1]
	v_cvt_pk_bf16_f32 v110, v118, v119
	v_cvt_pk_bf16_f32 v111, v120, v121
	v_cvt_pk_bf16_f32 v112, v112, v113
	v_cvt_pk_bf16_f32 v113, v122, v123
	global_store_dwordx4 v[152:153], v[110:113], off offset:256 sc1
	v_pk_mul_f32 v[114:115], v[144:145], v[114:115] op_sel_hi:[0,1]
	v_pk_mul_f32 v[102:103], v[144:145], v[102:103] op_sel_hi:[0,1]
	v_or_b32_e32 v110, 16, v151
	v_mul_lo_u32 v112, s19, v110
	v_mad_u64_u32 v[110:111], s[16:17], s18, v110, 0
	v_add3_u32 v111, v111, v0, v112
	v_lshl_add_u64 v[110:111], v[110:111], 1, v[146:147]
	v_pk_mul_f32 v[112:113], v[144:145], v[116:117] op_sel_hi:[0,1]
	v_pk_mul_f32 v[116:117], v[144:145], v[108:109] op_sel_hi:[0,1]
	v_pk_mul_f32 v[108:109], v[144:145], v[106:107] op_sel_hi:[0,1]
	v_cvt_pk_bf16_f32 v106, v114, v115
	v_cvt_pk_bf16_f32 v107, v112, v113
	v_cvt_pk_bf16_f32 v108, v108, v109
	v_cvt_pk_bf16_f32 v109, v116, v117
	global_store_dwordx4 v[110:111], v[106:109], off sc1
	v_pk_mul_f32 v[104:105], v[144:145], v[104:105] op_sel_hi:[0,1]
	v_pk_mul_f32 v[98:99], v[144:145], v[98:99] op_sel_hi:[0,1]
	v_pk_mul_f32 v[106:107], v[144:145], v[96:97] op_sel_hi:[0,1]
	v_pk_mul_f32 v[96:97], v[144:145], v[94:95] op_sel_hi:[0,1]
	v_cvt_pk_bf16_f32 v94, v102, v103
	v_cvt_pk_bf16_f32 v95, v104, v105
	v_cvt_pk_bf16_f32 v96, v96, v97
	v_cvt_pk_bf16_f32 v97, v106, v107
	global_store_dwordx4 v[110:111], v[94:97], off offset:256 sc1
	v_pk_mul_f32 v[86:87], v[144:145], v[86:87] op_sel_hi:[0,1]
	v_pk_mul_f32 v[88:89], v[144:145], v[88:89] op_sel_hi:[0,1]
	v_or_b32_e32 v94, 32, v151
	v_mul_lo_u32 v96, s19, v94
	v_mad_u64_u32 v[94:95], s[16:17], s18, v94, 0
	v_add3_u32 v95, v95, v0, v96
	v_lshl_add_u64 v[94:95], v[94:95], 1, v[146:147]
	v_pk_mul_f32 v[96:97], v[144:145], v[100:101] op_sel_hi:[0,1]
	v_pk_mul_f32 v[100:101], v[144:145], v[92:93] op_sel_hi:[0,1]
	v_pk_mul_f32 v[92:93], v[144:145], v[90:91] op_sel_hi:[0,1]
	v_cvt_pk_bf16_f32 v90, v98, v99
	v_cvt_pk_bf16_f32 v91, v96, v97
	v_cvt_pk_bf16_f32 v92, v92, v93
	v_cvt_pk_bf16_f32 v93, v100, v101
	global_store_dwordx4 v[94:95], v[90:93], off sc1
	v_pk_mul_f32 v[82:83], v[144:145], v[82:83] op_sel_hi:[0,1]
	v_pk_mul_f32 v[70:71], v[144:145], v[70:71] op_sel_hi:[0,1]
	v_pk_mul_f32 v[90:91], v[144:145], v[80:81] op_sel_hi:[0,1]
	v_pk_mul_f32 v[80:81], v[144:145], v[78:79] op_sel_hi:[0,1]
	v_cvt_pk_bf16_f32 v78, v86, v87
	v_cvt_pk_bf16_f32 v79, v88, v89
	v_cvt_pk_bf16_f32 v80, v80, v81
	v_cvt_pk_bf16_f32 v81, v90, v91
	global_store_dwordx4 v[94:95], v[78:81], off offset:256 sc1
	v_pk_mul_f32 v[72:73], v[144:145], v[72:73] op_sel_hi:[0,1]
	v_pk_mul_f32 v[64:65], v[144:145], v[64:65] op_sel_hi:[0,1]
	v_or_b32_e32 v78, 48, v151
	v_mul_lo_u32 v80, s19, v78
	v_mad_u64_u32 v[78:79], s[16:17], s18, v78, 0
	v_add3_u32 v79, v79, v0, v80
	v_lshl_add_u64 v[78:79], v[78:79], 1, v[146:147]
	v_pk_mul_f32 v[80:81], v[144:145], v[84:85] op_sel_hi:[0,1]
	v_pk_mul_f32 v[84:85], v[144:145], v[76:77] op_sel_hi:[0,1]
	v_pk_mul_f32 v[76:77], v[144:145], v[74:75] op_sel_hi:[0,1]
	v_cvt_pk_bf16_f32 v74, v82, v83
	v_cvt_pk_bf16_f32 v75, v80, v81
	v_cvt_pk_bf16_f32 v76, v76, v77
	v_cvt_pk_bf16_f32 v77, v84, v85
	global_store_dwordx4 v[78:79], v[74:77], off sc1
	v_add_u32_e32 v0, 0x80, v151
	v_pk_mul_f32 v[62:63], v[144:145], v[62:63] op_sel_hi:[0,1]
	v_pk_mul_f32 v[74:75], v[144:145], v[68:69] op_sel_hi:[0,1]
	v_pk_mul_f32 v[68:69], v[144:145], v[66:67] op_sel_hi:[0,1]
	v_cvt_pk_bf16_f32 v66, v70, v71
	v_cvt_pk_bf16_f32 v67, v72, v73
; __device__ __forceinline__ unsigned cvt_pk_bf16(float lo, float hi) { unsigned r; asm volatile("v_cvt_pk_bf16_f32 %0, %1, %2" : "=v"(r) : "v"(lo), "v"(hi)); return r; }
;     __device__ __forceinline__ void operator()(const f32x4 (&acc)[2][2][4][2], const Unit& u, int wr, int wc, int fr, int fq) const {
;     ...
;         const int row0 = u.pm * BM + wr * 64 + fr, col0 = colt + wc * 32 + 8 * fq;
;         const float sc = pn < 4 ? 0.125f * 1.4426950408889634f : 1.0f;
; #pragma unroll
;         for (int ai = 0; ai < 2; ++ai)
; #pragma unroll
;             for (int m = 0; m < 4; ++m) { bf16_t* rowp = base + (size_t)(row0 + ai * HALF + m * 16) * ldc + col0;
; #pragma unroll
;                 for (int bj = 0; bj < 2; ++bj) { const f32x4 v0 = acc[ai][bj][m][0] * sc, v1 = acc[ai][bj][m][1] * sc;
;                     u32x4 w; w.x = cvt_pk_bf16(v0[0], v0[1]); w.y = cvt_pk_bf16(v0[2], v0[3]); w.z = cvt_pk_bf16(v1[0], v1[1]); w.w = cvt_pk_bf16(v1[2], v1[3]);
;                     *(u32x4*)(rowp + bj * HALF) = w; } }
	v_cvt_pk_bf16_f32 v68, v68, v69
	v_cvt_pk_bf16_f32 v69, v74, v75
	global_store_dwordx4 v[78:79], v[66:69], off offset:256 sc1
	v_pk_mul_f32 v[54:55], v[144:145], v[54:55] op_sel_hi:[0,1]
	v_pk_mul_f32 v[56:57], v[144:145], v[56:57] op_sel_hi:[0,1]
	v_ashrrev_i32_e32 v66, 31, v0
	v_mul_lo_u32 v68, s18, v66
	v_mul_lo_u32 v69, s19, v0
	v_mad_u64_u32 v[66:67], s[16:17], s18, v0, 0
	v_add3_u32 v67, v67, v68, v69
	v_lshl_add_u64 v[66:67], v[66:67], 1, v[146:147]
	v_pk_mul_f32 v[68:69], v[144:145], v[60:61] op_sel_hi:[0,1]
	v_pk_mul_f32 v[60:61], v[144:145], v[58:59] op_sel_hi:[0,1]
	v_cvt_pk_bf16_f32 v58, v62, v63
	v_cvt_pk_bf16_f32 v59, v64, v65
	v_cvt_pk_bf16_f32 v60, v60, v61
	v_cvt_pk_bf16_f32 v61, v68, v69
	global_store_dwordx4 v[66:67], v[58:61], off sc1
	v_add_u32_e32 v0, 0x90, v151
	v_pk_mul_f32 v[48:49], v[144:145], v[48:49] op_sel_hi:[0,1]
	v_pk_mul_f32 v[58:59], v[144:145], v[52:53] op_sel_hi:[0,1]
	v_pk_mul_f32 v[52:53], v[144:145], v[50:51] op_sel_hi:[0,1]
	v_cvt_pk_bf16_f32 v50, v54, v55
	v_cvt_pk_bf16_f32 v51, v56, v57
	v_cvt_pk_bf16_f32 v52, v52, v53
	v_cvt_pk_bf16_f32 v53, v58, v59
	global_store_dwordx4 v[66:67], v[50:53], off offset:256 sc1
	v_pk_mul_f32 v[46:47], v[144:145], v[46:47] op_sel_hi:[0,1]
	v_pk_mul_f32 v[38:39], v[144:145], v[38:39] op_sel_hi:[0,1]
	v_ashrrev_i32_e32 v50, 31, v0
	v_mul_lo_u32 v52, s18, v50
	v_mul_lo_u32 v53, s19, v0
	v_mad_u64_u32 v[50:51], s[16:17], s18, v0, 0
	v_add3_u32 v51, v51, v52, v53
	v_lshl_add_u64 v[50:51], v[50:51], 1, v[146:147]
	v_pk_mul_f32 v[52:53], v[144:145], v[44:45] op_sel_hi:[0,1]
	v_pk_mul_f32 v[44:45], v[144:145], v[42:43] op_sel_hi:[0,1]
	v_cvt_pk_bf16_f32 v42, v46, v47
	v_cvt_pk_bf16_f32 v43, v48, v49
	v_cvt_pk_bf16_f32 v44, v44, v45
	v_cvt_pk_bf16_f32 v45, v52, v53
	global_store_dwordx4 v[50:51], v[42:45], off sc1
	v_add_u32_e32 v0, 0xa0, v151
	v_pk_mul_f32 v[40:41], v[144:145], v[40:41] op_sel_hi:[0,1]
	v_pk_mul_f32 v[42:43], v[144:145], v[36:37] op_sel_hi:[0,1]
	v_pk_mul_f32 v[36:37], v[144:145], v[34:35] op_sel_hi:[0,1]
	v_cvt_pk_bf16_f32 v34, v38, v39
	v_cvt_pk_bf16_f32 v35, v40, v41
	v_cvt_pk_bf16_f32 v36, v36, v37
	v_cvt_pk_bf16_f32 v37, v42, v43
	global_store_dwordx4 v[50:51], v[34:37], off offset:256 sc1
	v_pk_mul_f32 v[32:33], v[144:145], v[32:33] op_sel_hi:[0,1]
	v_pk_mul_f32 v[30:31], v[144:145], v[30:31] op_sel_hi:[0,1]
	v_ashrrev_i32_e32 v34, 31, v0
	v_mul_lo_u32 v36, s18, v34
	v_mul_lo_u32 v37, s19, v0
	v_mad_u64_u32 v[34:35], s[16:17], s18, v0, 0
	v_add3_u32 v35, v35, v36, v37
	v_lshl_add_u64 v[34:35], v[34:35], 1, v[146:147]
	v_pk_mul_f32 v[36:37], v[144:145], v[28:29] op_sel_hi:[0,1]
	v_pk_mul_f32 v[28:29], v[144:145], v[26:27] op_sel_hi:[0,1]
	v_cvt_pk_bf16_f32 v26, v30, v31
	v_cvt_pk_bf16_f32 v27, v32, v33
	v_cvt_pk_bf16_f32 v28, v28, v29
	v_cvt_pk_bf16_f32 v29, v36, v37
	global_store_dwordx4 v[34:35], v[26:29], off sc1
	v_pk_mul_f32 v[22:23], v[144:145], v[22:23] op_sel_hi:[0,1]
	v_add_u32_e32 v0, 0xb0, v151
	v_pk_mul_f32 v[26:27], v[144:145], v[20:21] op_sel_hi:[0,1]
	v_pk_mul_f32 v[20:21], v[144:145], v[18:19] op_sel_hi:[0,1]
	v_cvt_pk_bf16_f32 v18, v22, v23
	v_pk_mul_f32 v[24:25], v[144:145], v[24:25] op_sel_hi:[0,1]
	v_cvt_pk_bf16_f32 v19, v24, v25
	v_cvt_pk_bf16_f32 v20, v20, v21
	v_cvt_pk_bf16_f32 v21, v26, v27
	global_store_dwordx4 v[34:35], v[18:21], off offset:256 sc1
	v_pk_mul_f32 v[16:17], v[144:145], v[16:17] op_sel_hi:[0,1]
	v_pk_mul_f32 v[14:15], v[144:145], v[14:15] op_sel_hi:[0,1]
	v_ashrrev_i32_e32 v18, 31, v0
	v_mul_lo_u32 v20, s18, v18
	v_mul_lo_u32 v21, s19, v0
	v_mad_u64_u32 v[18:19], s[16:17], s18, v0, 0
	v_add3_u32 v19, v19, v20, v21
	v_lshl_add_u64 v[18:19], v[18:19], 1, v[146:147]
	v_pk_mul_f32 v[20:21], v[144:145], v[12:13] op_sel_hi:[0,1]
	v_pk_mul_f32 v[12:13], v[144:145], v[10:11] op_sel_hi:[0,1]
	v_cvt_pk_bf16_f32 v10, v14, v15
	v_cvt_pk_bf16_f32 v11, v16, v17
	v_readlane_b32 s42, v247, 0
	v_cvt_pk_bf16_f32 v12, v12, v13
	v_cvt_pk_bf16_f32 v13, v20, v21
	global_store_dwordx4 v[18:19], v[10:13], off sc1
	s_andn2_b64 vcc, exec, s[38:39]
	s_mov_b64 s[16:17], -1
	v_pk_mul_f32 v[10:11], v[144:145], v[4:5] op_sel_hi:[0,1]
	v_pk_mul_f32 v[4:5], v[144:145], v[2:3] op_sel_hi:[0,1]
	v_readlane_b32 s43, v247, 1
	v_pk_mul_f32 v[8:9], v[144:145], v[8:9] op_sel_hi:[0,1]
	v_pk_mul_f32 v[6:7], v[144:145], v[6:7] op_sel_hi:[0,1]
	v_cvt_pk_bf16_f32 v2, v6, v7
	v_cvt_pk_bf16_f32 v3, v8, v9
	v_cvt_pk_bf16_f32 v4, v4, v5
	v_cvt_pk_bf16_f32 v5, v10, v11
	global_store_dwordx4 v[18:19], v[2:5], off offset:256 sc1
	s_cbranch_vccnz .LBB0_75
	s_andn2_b64 vcc, exec, s[0:1]
	s_cbranch_vccnz .LBB0_74
	s_barrier
	s_branch .LBB0_74
